# GEMM compute segments: MFMAs reordered zig-zag over (m,n) so consecutive MFMAs share an operand register group more often
# speedup vs baseline: 1.0024x; 1.0004x over previous
; #define PG8_STAGE(bufoff, gbase, voff) do { _Pragma("unroll") for (int _i = 0; _i < 2; ++_i) \
;         __builtin_amdgcn_global_load_lds((const unsigned*)((const char*)(gbase) + (voff)[_i]), (LAS unsigned*)(lds + (bufoff) + ldsw + _i * 8192), 16, 0, 0); } while (0)
; #define PG8_LDA(dst, b, h) do { _Pragma("unroll") for (int m = 0; m < 4; ++m) _Pragma("unroll") for (int k = 0; k < 2; ++k) dst[m][k] = *(const LAS bf16x8*)(lds + PG8_SA(b, h) + aoff + m * 2048 + k * 1024); } while (0)
; #define PG8_LDB(dst, b, h) do { _Pragma("unroll") for (int n = 0; n < 2; ++n) _Pragma("unroll") for (int k = 0; k < 2; ++k) dst[n][k] = *(const LAS bf16x8*)(lds + PG8_SB(b, h) + boff + n * 2048 + k * 1024); } while (0)
; #define PG8_MMA(ai, bj, At, Bt) do { __builtin_amdgcn_s_setprio(1); _Pragma("unroll") for (int m = 0; m < 4; ++m) _Pragma("unroll") for (int n = 0; n < 2; ++n) _Pragma("unroll") for (int k = 0; k < 2; ++k) \
;         acc[ai][bj][m][n] = __builtin_amdgcn_mfma_f32_16x16x32_bf16(Bt[n][k], At[m][k], acc[ai][bj][m][n], 0, 0, 0); __builtin_amdgcn_s_setprio(0); } while (0)
; #define PG8_WAIT_V(n) asm volatile("s_waitcnt vmcnt(" #n ")" ::: "memory")
; #define PG8_WAIT_L(n) asm volatile("s_waitcnt lgkmcnt(" #n ")" ::: "memory")
; template <class Epi>
; __device__ __forceinline__ void gemm_phase(LAS unsigned char* lds, const Gemm g, const StaticOrder& S, const Epi& E) {
;     ...
;         for (int t = 0; t < nt; t += 2) {
;             const bool last = (t == nt - 2);
;             const char* a1 = cA + (size_t)(t + 1) * kstep;
;             const char* a2 = last ? nA : cA + (size_t)(t + 2) * kstep; const char* b2 = last ? nB : cB + (size_t)(t + 2) * kstep;
;             const char* a3 = a2 + kstep; const char* b3 = b2 + kstep;
;             PG8_LDB(B0, 0, 0); PG8_SCHED; PG8_LDA(At, 0, 0); PG8_STAGE(PG8_SA(1, 1), a1 + hstep, voffA);
;             PG8_WAIT_L(8); PG8_BAR; PG8_WAIT_L(0); PG8_MMA(0, 0, At, B0); PG8_BAR; PG8_SCHED;
;             PG8_LDB(B1, 0, 1); PG8_STAGE(PG8_SB(0, 0), b2, voffB);
;             PG8_BAR; PG8_WAIT_L(0); PG8_MMA(0, 1, At, B1); PG8_BAR;
;             PG8_LDA(At, 0, 1); PG8_STAGE(PG8_SA(0, 0), a2, voffA);
;             PG8_BAR; PG8_WAIT_L(0); PG8_MMA(1, 0, At, B0); PG8_BAR; PG8_SCHED;
;             PG8_STAGE(PG8_SB(0, 1), b2 + hstep, voffB);
;             PG8_WAIT_V(6); PG8_BAR; PG8_MMA(1, 1, At, B1); PG8_BAR;
.LBB0_119:
	s_add_i32 s41, s16, 2
	s_add_u32 s18, s14, 0x80
	s_addc_u32 s17, s15, 0
	ds_read_b128 v[128:131], v224
	ds_read_b128 v[132:135], v224 offset:1024
	ds_read_b128 v[136:139], v224 offset:2048
	ds_read_b128 v[140:143], v224 offset:3072
	s_cmp_eq_u32 s31, s16
	s_cselect_b32 s16, s10, s18
	s_cselect_b32 s17, s11, s17
	s_cselect_b32 s19, s13, s40
	s_cselect_b32 s18, s12, s39
	s_add_i32 m0, s24, 0xc000
	ds_read_b128 v[144:147], v247
	ds_read_b128 v[148:151], v247 offset:1024
	ds_read_b128 v[152:155], v247 offset:2048
	ds_read_b128 v[156:159], v247 offset:3072
	ds_read_b128 v[160:163], v247 offset:4096
	ds_read_b128 v[164:167], v247 offset:5120
	ds_read_b128 v[168:171], v247 offset:6144
	global_load_lds_dwordx4 v210, s[14:15]
	s_add_i32 m0, s24, 0xe000
	ds_read_b128 v[172:175], v247 offset:7168
	global_load_lds_dwordx4 v208, s[14:15]
	s_waitcnt lgkmcnt(8)
	s_barrier
	s_waitcnt lgkmcnt(0)
	v_mfma_f32_16x16x32_bf16 v[124:127], v[128:131], v[144:147], v[124:127]
	v_mfma_f32_16x16x32_bf16 v[120:123], v[136:139], v[144:147], v[120:123]
	v_mfma_f32_16x16x32_bf16 v[104:107], v[136:139], v[152:155], v[104:107]
	v_mfma_f32_16x16x32_bf16 v[108:111], v[128:131], v[152:155], v[108:111]
	v_mfma_f32_16x16x32_bf16 v[92:95], v[128:131], v[160:163], v[92:95]
	v_mfma_f32_16x16x32_bf16 v[88:91], v[136:139], v[160:163], v[88:91]
	v_mfma_f32_16x16x32_bf16 v[72:75], v[136:139], v[168:171], v[72:75]
	v_mfma_f32_16x16x32_bf16 v[76:79], v[128:131], v[168:171], v[76:79]
	v_mfma_f32_16x16x32_bf16 v[124:127], v[132:135], v[148:151], v[124:127]
	v_mfma_f32_16x16x32_bf16 v[120:123], v[140:143], v[148:151], v[120:123]
	v_mfma_f32_16x16x32_bf16 v[104:107], v[140:143], v[156:159], v[104:107]
	v_mfma_f32_16x16x32_bf16 v[108:111], v[132:135], v[156:159], v[108:111]
	v_mfma_f32_16x16x32_bf16 v[92:95], v[132:135], v[164:167], v[92:95]
	v_mfma_f32_16x16x32_bf16 v[88:91], v[140:143], v[164:167], v[88:91]
	v_mfma_f32_16x16x32_bf16 v[72:75], v[140:143], v[172:175], v[72:75]
	v_mfma_f32_16x16x32_bf16 v[76:79], v[132:135], v[172:175], v[76:79]
	s_barrier
	s_add_u32 s80, s18, 0x80
	s_addc_u32 s81, s19, 0
	s_mov_b32 m0, s86
	ds_read_b128 v[176:179], v225
	ds_read_b128 v[180:183], v225 offset:1024
	ds_read_b128 v[184:187], v225 offset:2048
	global_load_lds_dwordx4 v194, s[18:19]
	s_add_i32 m0, s86, 0x2000
	ds_read_b128 v[188:191], v225 offset:3072
	global_load_lds_dwordx4 v206, s[18:19]
	s_barrier
	s_waitcnt lgkmcnt(0)
	v_mfma_f32_16x16x32_bf16 v[116:119], v[176:179], v[144:147], v[116:119]
	v_mfma_f32_16x16x32_bf16 v[112:115], v[184:187], v[144:147], v[112:115]
	v_mfma_f32_16x16x32_bf16 v[96:99], v[184:187], v[152:155], v[96:99]
	v_mfma_f32_16x16x32_bf16 v[100:103], v[176:179], v[152:155], v[100:103]
	v_mfma_f32_16x16x32_bf16 v[84:87], v[176:179], v[160:163], v[84:87]
	v_mfma_f32_16x16x32_bf16 v[80:83], v[184:187], v[160:163], v[80:83]
	v_mfma_f32_16x16x32_bf16 v[64:67], v[184:187], v[168:171], v[64:67]
	v_mfma_f32_16x16x32_bf16 v[68:71], v[176:179], v[168:171], v[68:71]
	v_mfma_f32_16x16x32_bf16 v[116:119], v[180:183], v[148:151], v[116:119]
	v_mfma_f32_16x16x32_bf16 v[112:115], v[188:191], v[148:151], v[112:115]
	v_mfma_f32_16x16x32_bf16 v[96:99], v[188:191], v[156:159], v[96:99]
	v_mfma_f32_16x16x32_bf16 v[100:103], v[180:183], v[156:159], v[100:103]
	v_mfma_f32_16x16x32_bf16 v[84:87], v[180:183], v[164:167], v[84:87]
	v_mfma_f32_16x16x32_bf16 v[80:83], v[188:191], v[164:167], v[80:83]
	v_mfma_f32_16x16x32_bf16 v[64:67], v[188:191], v[172:175], v[64:67]
	v_mfma_f32_16x16x32_bf16 v[68:71], v[180:183], v[172:175], v[68:71]
	s_mov_b32 m0, s24
	s_add_u32 s82, s16, 0x80
	s_addc_u32 s83, s17, 0
	s_barrier
	ds_read_b128 v[144:147], v247 offset:16384
	ds_read_b128 v[148:151], v247 offset:17408
	ds_read_b128 v[152:155], v247 offset:18432
	ds_read_b128 v[156:159], v247 offset:19456
	ds_read_b128 v[160:163], v247 offset:20480
	ds_read_b128 v[164:167], v247 offset:21504
	ds_read_b128 v[168:171], v247 offset:22528
	global_load_lds_dwordx4 v202, s[16:17]
	s_mov_b32 m0, s25
	ds_read_b128 v[172:175], v247 offset:23552
	global_load_lds_dwordx4 v204, s[16:17]
	s_barrier
	s_waitcnt lgkmcnt(0)
	v_mfma_f32_16x16x32_bf16 v[60:63], v[128:131], v[144:147], v[60:63]
	v_mfma_f32_16x16x32_bf16 v[56:59], v[136:139], v[144:147], v[56:59]
	v_mfma_f32_16x16x32_bf16 v[40:43], v[136:139], v[152:155], v[40:43]
	v_mfma_f32_16x16x32_bf16 v[44:47], v[128:131], v[152:155], v[44:47]
	v_mfma_f32_16x16x32_bf16 v[28:31], v[128:131], v[160:163], v[28:31]
	v_mfma_f32_16x16x32_bf16 v[24:27], v[136:139], v[160:163], v[24:27]
	v_mfma_f32_16x16x32_bf16 v[8:11], v[136:139], v[168:171], v[8:11]
	v_mfma_f32_16x16x32_bf16 v[12:15], v[128:131], v[168:171], v[12:15]
	v_mfma_f32_16x16x32_bf16 v[60:63], v[132:135], v[148:151], v[60:63]
	v_mfma_f32_16x16x32_bf16 v[56:59], v[140:143], v[148:151], v[56:59]
	v_mfma_f32_16x16x32_bf16 v[40:43], v[140:143], v[156:159], v[40:43]
	v_mfma_f32_16x16x32_bf16 v[44:47], v[132:135], v[156:159], v[44:47]
	v_mfma_f32_16x16x32_bf16 v[28:31], v[132:135], v[164:167], v[28:31]
	v_mfma_f32_16x16x32_bf16 v[24:27], v[140:143], v[164:167], v[24:27]
	v_mfma_f32_16x16x32_bf16 v[8:11], v[140:143], v[172:175], v[8:11]
	v_mfma_f32_16x16x32_bf16 v[12:15], v[132:135], v[172:175], v[12:15]
	s_barrier
	s_add_u32 s18, s18, s0
	s_addc_u32 s19, s19, s1
	s_add_u32 s84, s18, 0x80
	s_mov_b32 m0, s87
	s_addc_u32 s85, s19, 0
	global_load_lds_dwordx4 v194, s[18:19]
	s_add_i32 m0, s87, 0x2000
	s_nop 0
	global_load_lds_dwordx4 v206, s[18:19]
	s_waitcnt vmcnt(6)
	s_barrier
; #define PG8_STAGE(bufoff, gbase, voff) do { _Pragma("unroll") for (int _i = 0; _i < 2; ++_i) \
;         __builtin_amdgcn_global_load_lds((const unsigned*)((const char*)(gbase) + (voff)[_i]), (LAS unsigned*)(lds + (bufoff) + ldsw + _i * 8192), 16, 0, 0); } while (0)
; #define PG8_LDA(dst, b, h) do { _Pragma("unroll") for (int m = 0; m < 4; ++m) _Pragma("unroll") for (int k = 0; k < 2; ++k) dst[m][k] = *(const LAS bf16x8*)(lds + PG8_SA(b, h) + aoff + m * 2048 + k * 1024); } while (0)
; #define PG8_LDB(dst, b, h) do { _Pragma("unroll") for (int n = 0; n < 2; ++n) _Pragma("unroll") for (int k = 0; k < 2; ++k) dst[n][k] = *(const LAS bf16x8*)(lds + PG8_SB(b, h) + boff + n * 2048 + k * 1024); } while (0)
; #define PG8_MMA(ai, bj, At, Bt) do { __builtin_amdgcn_s_setprio(1); _Pragma("unroll") for (int m = 0; m < 4; ++m) _Pragma("unroll") for (int n = 0; n < 2; ++n) _Pragma("unroll") for (int k = 0; k < 2; ++k) \
;         acc[ai][bj][m][n] = __builtin_amdgcn_mfma_f32_16x16x32_bf16(Bt[n][k], At[m][k], acc[ai][bj][m][n], 0, 0, 0); __builtin_amdgcn_s_setprio(0); } while (0)
; #define PG8_WAIT_V(n) asm volatile("s_waitcnt vmcnt(" #n ")" ::: "memory")
; #define PG8_WAIT_L(n) asm volatile("s_waitcnt lgkmcnt(" #n ")" ::: "memory")
; #define PG8_BAR __builtin_amdgcn_s_barrier()
; #define PG8_SCHED __builtin_amdgcn_sched_barrier(0)
; template <class Epi>
; __device__ __forceinline__ void gemm_phase(LAS unsigned char* lds, const Gemm g, const StaticOrder& S, const Epi& E) {
;     ...
;             PG8_WAIT_V(6); PG8_BAR; PG8_MMA(1, 1, At, B1); PG8_BAR;
;             PG8_LDB(B0, 1, 0); PG8_SCHED; PG8_LDA(At, 1, 0); PG8_STAGE(PG8_SA(0, 1), a2 + hstep, voffA);
;             PG8_WAIT_L(8); PG8_BAR; PG8_WAIT_L(0); PG8_MMA(0, 0, At, B0); PG8_BAR; PG8_SCHED;
;             PG8_LDB(B1, 1, 1); PG8_STAGE(PG8_SB(1, 0), b3, voffB);
;             PG8_BAR; PG8_WAIT_L(0); PG8_MMA(0, 1, At, B1); PG8_BAR;
	v_mfma_f32_16x16x32_bf16 v[52:55], v[176:179], v[144:147], v[52:55]
	v_mfma_f32_16x16x32_bf16 v[48:51], v[184:187], v[144:147], v[48:51]
	v_mfma_f32_16x16x32_bf16 v[32:35], v[184:187], v[152:155], v[32:35]
	v_mfma_f32_16x16x32_bf16 v[36:39], v[176:179], v[152:155], v[36:39]
	v_mfma_f32_16x16x32_bf16 v[20:23], v[176:179], v[160:163], v[20:23]
	v_mfma_f32_16x16x32_bf16 v[16:19], v[184:187], v[160:163], v[16:19]
	v_mfma_f32_16x16x32_bf16 v[0:3], v[184:187], v[168:171], v[0:3]
	v_mfma_f32_16x16x32_bf16 v[4:7], v[176:179], v[168:171], v[4:7]
	v_mfma_f32_16x16x32_bf16 v[52:55], v[180:183], v[148:151], v[52:55]
	v_mfma_f32_16x16x32_bf16 v[48:51], v[188:191], v[148:151], v[48:51]
	v_mfma_f32_16x16x32_bf16 v[32:35], v[188:191], v[156:159], v[32:35]
	v_mfma_f32_16x16x32_bf16 v[36:39], v[180:183], v[156:159], v[36:39]
	v_mfma_f32_16x16x32_bf16 v[20:23], v[180:183], v[164:167], v[20:23]
	v_mfma_f32_16x16x32_bf16 v[16:19], v[188:191], v[164:167], v[16:19]
	v_mfma_f32_16x16x32_bf16 v[0:3], v[188:191], v[172:175], v[0:3]
	v_mfma_f32_16x16x32_bf16 v[4:7], v[180:183], v[172:175], v[4:7]
	s_barrier
	ds_read_b128 v[128:131], v226
	ds_read_b128 v[132:135], v226 offset:1024
	ds_read_b128 v[136:139], v226 offset:2048
	ds_read_b128 v[140:143], v226 offset:3072
	s_add_u32 s16, s16, s0
	s_addc_u32 s17, s17, s1
	s_mov_b32 m0, s26
	ds_read_b128 v[144:147], v247 offset:32768
	ds_read_b128 v[148:151], v247 offset:33792
	ds_read_b128 v[152:155], v247 offset:34816
	ds_read_b128 v[156:159], v247 offset:35840
	ds_read_b128 v[160:163], v247 offset:36864
	ds_read_b128 v[164:167], v247 offset:37888
	ds_read_b128 v[168:171], v247 offset:38912
	global_load_lds_dwordx4 v202, s[16:17]
	s_mov_b32 m0, s27
	ds_read_b128 v[172:175], v247 offset:39936
	global_load_lds_dwordx4 v204, s[16:17]
	s_waitcnt lgkmcnt(8)
	s_barrier
	s_waitcnt lgkmcnt(0)
	v_mfma_f32_16x16x32_bf16 v[124:127], v[128:131], v[144:147], v[124:127]
	v_mfma_f32_16x16x32_bf16 v[120:123], v[136:139], v[144:147], v[120:123]
	v_mfma_f32_16x16x32_bf16 v[104:107], v[136:139], v[152:155], v[104:107]
	v_mfma_f32_16x16x32_bf16 v[108:111], v[128:131], v[152:155], v[108:111]
	v_mfma_f32_16x16x32_bf16 v[92:95], v[128:131], v[160:163], v[92:95]
	v_mfma_f32_16x16x32_bf16 v[88:91], v[136:139], v[160:163], v[88:91]
	v_mfma_f32_16x16x32_bf16 v[72:75], v[136:139], v[168:171], v[72:75]
	v_mfma_f32_16x16x32_bf16 v[76:79], v[128:131], v[168:171], v[76:79]
	v_mfma_f32_16x16x32_bf16 v[124:127], v[132:135], v[148:151], v[124:127]
	v_mfma_f32_16x16x32_bf16 v[120:123], v[140:143], v[148:151], v[120:123]
	v_mfma_f32_16x16x32_bf16 v[104:107], v[140:143], v[156:159], v[104:107]
	v_mfma_f32_16x16x32_bf16 v[108:111], v[132:135], v[156:159], v[108:111]
	v_mfma_f32_16x16x32_bf16 v[92:95], v[132:135], v[164:167], v[92:95]
	v_mfma_f32_16x16x32_bf16 v[88:91], v[140:143], v[164:167], v[88:91]
	v_mfma_f32_16x16x32_bf16 v[72:75], v[140:143], v[172:175], v[72:75]
	v_mfma_f32_16x16x32_bf16 v[76:79], v[132:135], v[172:175], v[76:79]
	s_barrier
	s_mov_b32 m0, s88
	ds_read_b128 v[176:179], v227
	ds_read_b128 v[180:183], v227 offset:1024
	ds_read_b128 v[184:187], v227 offset:2048
	global_load_lds_dwordx4 v194, s[80:81]
	s_add_i32 m0, s88, 0x2000
	ds_read_b128 v[188:191], v227 offset:3072
	global_load_lds_dwordx4 v206, s[80:81]
	s_barrier
; #define PG8_STAGE(bufoff, gbase, voff) do { _Pragma("unroll") for (int _i = 0; _i < 2; ++_i) \
;         __builtin_amdgcn_global_load_lds((const unsigned*)((const char*)(gbase) + (voff)[_i]), (LAS unsigned*)(lds + (bufoff) + ldsw + _i * 8192), 16, 0, 0); } while (0)
; #define PG8_LDA(dst, b, h) do { _Pragma("unroll") for (int m = 0; m < 4; ++m) _Pragma("unroll") for (int k = 0; k < 2; ++k) dst[m][k] = *(const LAS bf16x8*)(lds + PG8_SA(b, h) + aoff + m * 2048 + k * 1024); } while (0)
; #define PG8_MMA(ai, bj, At, Bt) do { __builtin_amdgcn_s_setprio(1); _Pragma("unroll") for (int m = 0; m < 4; ++m) _Pragma("unroll") for (int n = 0; n < 2; ++n) _Pragma("unroll") for (int k = 0; k < 2; ++k) \
;         acc[ai][bj][m][n] = __builtin_amdgcn_mfma_f32_16x16x32_bf16(Bt[n][k], At[m][k], acc[ai][bj][m][n], 0, 0, 0); __builtin_amdgcn_s_setprio(0); } while (0)
; #define PG8_WAIT_V(n) asm volatile("s_waitcnt vmcnt(" #n ")" ::: "memory")
; #define PG8_WAIT_L(n) asm volatile("s_waitcnt lgkmcnt(" #n ")" ::: "memory")
; #define PG8_BAR __builtin_amdgcn_s_barrier()
; #define PG8_SCHED __builtin_amdgcn_sched_barrier(0)
; template <class Epi>
; __device__ __forceinline__ void gemm_phase(LAS unsigned char* lds, const Gemm g, const StaticOrder& S, const Epi& E) {
;     ...
;             PG8_BAR; PG8_WAIT_L(0); PG8_MMA(0, 1, At, B1); PG8_BAR;
;             PG8_LDA(At, 1, 1); PG8_STAGE(PG8_SA(1, 0), a3, voffA);
;             PG8_BAR; PG8_WAIT_L(0); PG8_MMA(1, 0, At, B0); PG8_BAR; PG8_SCHED;
;             PG8_STAGE(PG8_SB(1, 1), b3 + hstep, voffB);
;             PG8_WAIT_V(6); PG8_BAR; PG8_MMA(1, 1, At, B1); PG8_BAR;
	s_waitcnt lgkmcnt(0)
	v_mfma_f32_16x16x32_bf16 v[116:119], v[176:179], v[144:147], v[116:119]
	v_mfma_f32_16x16x32_bf16 v[112:115], v[184:187], v[144:147], v[112:115]
	v_mfma_f32_16x16x32_bf16 v[96:99], v[184:187], v[152:155], v[96:99]
	v_mfma_f32_16x16x32_bf16 v[100:103], v[176:179], v[152:155], v[100:103]
	v_mfma_f32_16x16x32_bf16 v[84:87], v[176:179], v[160:163], v[84:87]
	v_mfma_f32_16x16x32_bf16 v[80:83], v[184:187], v[160:163], v[80:83]
	v_mfma_f32_16x16x32_bf16 v[64:67], v[184:187], v[168:171], v[64:67]
	v_mfma_f32_16x16x32_bf16 v[68:71], v[176:179], v[168:171], v[68:71]
	v_mfma_f32_16x16x32_bf16 v[116:119], v[180:183], v[148:151], v[116:119]
	v_mfma_f32_16x16x32_bf16 v[112:115], v[188:191], v[148:151], v[112:115]
	v_mfma_f32_16x16x32_bf16 v[96:99], v[188:191], v[156:159], v[96:99]
	v_mfma_f32_16x16x32_bf16 v[100:103], v[180:183], v[156:159], v[100:103]
	v_mfma_f32_16x16x32_bf16 v[84:87], v[180:183], v[164:167], v[84:87]
	v_mfma_f32_16x16x32_bf16 v[80:83], v[188:191], v[164:167], v[80:83]
	v_mfma_f32_16x16x32_bf16 v[64:67], v[188:191], v[172:175], v[64:67]
	v_mfma_f32_16x16x32_bf16 v[68:71], v[180:183], v[172:175], v[68:71]
	s_mov_b32 m0, s28
	s_barrier
	ds_read_b128 v[144:147], v247 offset:49152
	ds_read_b128 v[148:151], v247 offset:50176
	ds_read_b128 v[152:155], v247 offset:51200
	ds_read_b128 v[156:159], v247 offset:52224
	ds_read_b128 v[160:163], v247 offset:53248
	ds_read_b128 v[164:167], v247 offset:54272
	ds_read_b128 v[168:171], v247 offset:55296
	global_load_lds_dwordx4 v202, s[82:83]
	s_mov_b32 m0, s29
	ds_read_b128 v[172:175], v247 offset:56320
	global_load_lds_dwordx4 v204, s[82:83]
	s_barrier
	s_waitcnt lgkmcnt(0)
	v_mfma_f32_16x16x32_bf16 v[60:63], v[128:131], v[144:147], v[60:63]
	v_mfma_f32_16x16x32_bf16 v[56:59], v[136:139], v[144:147], v[56:59]
	v_mfma_f32_16x16x32_bf16 v[40:43], v[136:139], v[152:155], v[40:43]
	v_mfma_f32_16x16x32_bf16 v[44:47], v[128:131], v[152:155], v[44:47]
	v_mfma_f32_16x16x32_bf16 v[28:31], v[128:131], v[160:163], v[28:31]
	v_mfma_f32_16x16x32_bf16 v[24:27], v[136:139], v[160:163], v[24:27]
	v_mfma_f32_16x16x32_bf16 v[8:11], v[136:139], v[168:171], v[8:11]
	v_mfma_f32_16x16x32_bf16 v[12:15], v[128:131], v[168:171], v[12:15]
	v_mfma_f32_16x16x32_bf16 v[60:63], v[132:135], v[148:151], v[60:63]
	v_mfma_f32_16x16x32_bf16 v[56:59], v[140:143], v[148:151], v[56:59]
	v_mfma_f32_16x16x32_bf16 v[40:43], v[140:143], v[156:159], v[40:43]
	v_mfma_f32_16x16x32_bf16 v[44:47], v[132:135], v[156:159], v[44:47]
	v_mfma_f32_16x16x32_bf16 v[28:31], v[132:135], v[164:167], v[28:31]
	v_mfma_f32_16x16x32_bf16 v[24:27], v[140:143], v[164:167], v[24:27]
	v_mfma_f32_16x16x32_bf16 v[8:11], v[140:143], v[172:175], v[8:11]
	v_mfma_f32_16x16x32_bf16 v[12:15], v[132:135], v[172:175], v[12:15]
	s_barrier
	s_mov_b32 m0, s89
	s_nop 0
	global_load_lds_dwordx4 v194, s[84:85]
	s_add_i32 m0, s89, 0x2000
	s_nop 0
	global_load_lds_dwordx4 v206, s[84:85]
	s_waitcnt vmcnt(6)
	s_barrier
	v_mfma_f32_16x16x32_bf16 v[52:55], v[176:179], v[144:147], v[52:55]
	v_mfma_f32_16x16x32_bf16 v[48:51], v[184:187], v[144:147], v[48:51]
	v_mfma_f32_16x16x32_bf16 v[32:35], v[184:187], v[152:155], v[32:35]
	v_mfma_f32_16x16x32_bf16 v[36:39], v[176:179], v[152:155], v[36:39]
	v_mfma_f32_16x16x32_bf16 v[20:23], v[176:179], v[160:163], v[20:23]
	v_mfma_f32_16x16x32_bf16 v[16:19], v[184:187], v[160:163], v[16:19]
	v_mfma_f32_16x16x32_bf16 v[0:3], v[184:187], v[168:171], v[0:3]
	v_mfma_f32_16x16x32_bf16 v[4:7], v[176:179], v[168:171], v[4:7]
	v_mfma_f32_16x16x32_bf16 v[52:55], v[180:183], v[148:151], v[52:55]
	v_mfma_f32_16x16x32_bf16 v[48:51], v[188:191], v[148:151], v[48:51]
	v_mfma_f32_16x16x32_bf16 v[32:35], v[188:191], v[156:159], v[32:35]
	v_mfma_f32_16x16x32_bf16 v[36:39], v[180:183], v[156:159], v[36:39]
	v_mfma_f32_16x16x32_bf16 v[20:23], v[180:183], v[164:167], v[20:23]
	v_mfma_f32_16x16x32_bf16 v[16:19], v[188:191], v[164:167], v[16:19]
	v_mfma_f32_16x16x32_bf16 v[0:3], v[188:191], v[172:175], v[0:3]
	v_mfma_f32_16x16x32_bf16 v[4:7], v[180:183], v[172:175], v[4:7]
	s_add_u32 s39, s39, 0x100
	s_addc_u32 s40, s40, 0
	s_add_u32 s14, s14, 0x100
	s_addc_u32 s15, s15, 0
	s_cmp_ge_i32 s41, s30
	s_mov_b32 s16, s41
	s_barrier
	s_cbranch_scc0 .LBB0_119

; #define PG8_STAGE(bufoff, gbase, voff) do { _Pragma("unroll") for (int _i = 0; _i < 2; ++_i) \
;         __builtin_amdgcn_global_load_lds((const unsigned*)((const char*)(gbase) + (voff)[_i]), (LAS unsigned*)(lds + (bufoff) + ldsw + _i * 8192), 16, 0, 0); } while (0)
; #define PG8_LDA(dst, b, h) do { _Pragma("unroll") for (int m = 0; m < 4; ++m) _Pragma("unroll") for (int k = 0; k < 2; ++k) dst[m][k] = *(const LAS bf16x8*)(lds + PG8_SA(b, h) + aoff + m * 2048 + k * 1024); } while (0)
; #define PG8_LDB(dst, b, h) do { _Pragma("unroll") for (int n = 0; n < 2; ++n) _Pragma("unroll") for (int k = 0; k < 2; ++k) dst[n][k] = *(const LAS bf16x8*)(lds + PG8_SB(b, h) + boff + n * 2048 + k * 1024); } while (0)
; #define PG8_MMA(ai, bj, At, Bt) do { __builtin_amdgcn_s_setprio(1); _Pragma("unroll") for (int m = 0; m < 4; ++m) _Pragma("unroll") for (int n = 0; n < 2; ++n) _Pragma("unroll") for (int k = 0; k < 2; ++k) \
;         acc[ai][bj][m][n] = __builtin_amdgcn_mfma_f32_16x16x32_bf16(Bt[n][k], At[m][k], acc[ai][bj][m][n], 0, 0, 0); __builtin_amdgcn_s_setprio(0); } while (0)
; #define PG8_WAIT_V(n) asm volatile("s_waitcnt vmcnt(" #n ")" ::: "memory")
; #define PG8_WAIT_L(n) asm volatile("s_waitcnt lgkmcnt(" #n ")" ::: "memory")
; template <class Epi>
; __device__ __forceinline__ void gemm_phase(LAS unsigned char* lds, const Gemm g, const StaticOrder& S, const Epi& E) {
;     ...
;         for (int t = 0; t < nt; t += 2) {
;             const bool last = (t == nt - 2);
;             const char* a1 = cA + (size_t)(t + 1) * kstep;
;             const char* a2 = last ? nA : cA + (size_t)(t + 2) * kstep; const char* b2 = last ? nB : cB + (size_t)(t + 2) * kstep;
;             const char* a3 = a2 + kstep; const char* b3 = b2 + kstep;
;             PG8_LDB(B0, 0, 0); PG8_SCHED; PG8_LDA(At, 0, 0); PG8_STAGE(PG8_SA(1, 1), a1 + hstep, voffA);
;             PG8_WAIT_L(8); PG8_BAR; PG8_WAIT_L(0); PG8_MMA(0, 0, At, B0); PG8_BAR; PG8_SCHED;
;             PG8_LDB(B1, 0, 1); PG8_STAGE(PG8_SB(0, 0), b2, voffB);
;             PG8_BAR; PG8_WAIT_L(0); PG8_MMA(0, 1, At, B1); PG8_BAR;
;             PG8_LDA(At, 0, 1); PG8_STAGE(PG8_SA(0, 0), a2, voffA);
;             PG8_BAR; PG8_WAIT_L(0); PG8_MMA(1, 0, At, B0); PG8_BAR; PG8_SCHED;
;             PG8_STAGE(PG8_SB(0, 1), b2 + hstep, voffB);
;             PG8_WAIT_V(6); PG8_BAR; PG8_MMA(1, 1, At, B1); PG8_BAR;
.LBB0_165:
	s_add_i32 s44, s18, 2
	s_add_u32 s20, s16, 0x80
	s_addc_u32 s19, s17, 0
	ds_read_b128 v[138:141], v224
	ds_read_b128 v[152:155], v224 offset:1024
	ds_read_b128 v[156:159], v224 offset:2048
	ds_read_b128 v[160:163], v224 offset:3072
	s_cmp_eq_u32 s35, s18
	s_cselect_b32 s18, s10, s20
	s_cselect_b32 s19, s11, s19
	s_cselect_b32 s21, s13, s43
	s_cselect_b32 s20, s12, s42
	s_add_i32 m0, s27, 0xc000
	ds_read_b128 v[164:167], v150
	ds_read_b128 v[168:171], v150 offset:1024
	ds_read_b128 v[172:175], v150 offset:2048
	ds_read_b128 v[176:179], v150 offset:3072
	ds_read_b128 v[180:183], v150 offset:4096
	ds_read_b128 v[184:187], v150 offset:5120
	ds_read_b128 v[188:191], v150 offset:6144
	global_load_lds_dwordx4 v136, s[16:17]
	s_add_i32 m0, s27, 0xe000
	ds_read_b128 v[202:205], v150 offset:7168
	global_load_lds_dwordx4 v134, s[16:17]
	s_waitcnt lgkmcnt(8)
	s_barrier
	s_waitcnt lgkmcnt(0)
	v_mfma_f32_16x16x32_bf16 v[124:127], v[138:141], v[164:167], v[124:127]
	v_mfma_f32_16x16x32_bf16 v[120:123], v[156:159], v[164:167], v[120:123]
	v_mfma_f32_16x16x32_bf16 v[104:107], v[156:159], v[172:175], v[104:107]
	v_mfma_f32_16x16x32_bf16 v[108:111], v[138:141], v[172:175], v[108:111]
	v_mfma_f32_16x16x32_bf16 v[92:95], v[138:141], v[180:183], v[92:95]
	v_mfma_f32_16x16x32_bf16 v[88:91], v[156:159], v[180:183], v[88:91]
	v_mfma_f32_16x16x32_bf16 v[72:75], v[156:159], v[188:191], v[72:75]
	v_mfma_f32_16x16x32_bf16 v[76:79], v[138:141], v[188:191], v[76:79]
	v_mfma_f32_16x16x32_bf16 v[124:127], v[152:155], v[168:171], v[124:127]
	v_mfma_f32_16x16x32_bf16 v[120:123], v[160:163], v[168:171], v[120:123]
	v_mfma_f32_16x16x32_bf16 v[104:107], v[160:163], v[176:179], v[104:107]
	v_mfma_f32_16x16x32_bf16 v[108:111], v[152:155], v[176:179], v[108:111]
	v_mfma_f32_16x16x32_bf16 v[92:95], v[152:155], v[184:187], v[92:95]
	v_mfma_f32_16x16x32_bf16 v[88:91], v[160:163], v[184:187], v[88:91]
	v_mfma_f32_16x16x32_bf16 v[72:75], v[160:163], v[202:205], v[72:75]
	v_mfma_f32_16x16x32_bf16 v[76:79], v[152:155], v[202:205], v[76:79]
	s_barrier
	ds_read_b128 v[206:209], v225
	ds_read_b128 v[210:213], v225 offset:1024
	s_add_u32 s80, s20, 0x80
	s_addc_u32 s81, s21, 0
	s_mov_b32 m0, s86
	ds_read_b128 v[218:221], v225 offset:3072
	global_load_lds_dwordx4 v194, s[20:21]
	s_add_i32 m0, s86, 0x2000
	ds_read_b128 v[214:217], v225 offset:2048
	global_load_lds_dwordx4 v132, s[20:21]
	s_barrier
	s_waitcnt lgkmcnt(0)
	v_mfma_f32_16x16x32_bf16 v[116:119], v[206:209], v[164:167], v[116:119]
	v_mfma_f32_16x16x32_bf16 v[112:115], v[214:217], v[164:167], v[112:115]
	v_mfma_f32_16x16x32_bf16 v[96:99], v[214:217], v[172:175], v[96:99]
	v_mfma_f32_16x16x32_bf16 v[100:103], v[206:209], v[172:175], v[100:103]
	v_mfma_f32_16x16x32_bf16 v[84:87], v[206:209], v[180:183], v[84:87]
	v_mfma_f32_16x16x32_bf16 v[80:83], v[214:217], v[180:183], v[80:83]
	v_mfma_f32_16x16x32_bf16 v[64:67], v[214:217], v[188:191], v[64:67]
	v_mfma_f32_16x16x32_bf16 v[68:71], v[206:209], v[188:191], v[68:71]
	v_mfma_f32_16x16x32_bf16 v[116:119], v[210:213], v[168:171], v[116:119]
	v_mfma_f32_16x16x32_bf16 v[112:115], v[218:221], v[168:171], v[112:115]
	v_mfma_f32_16x16x32_bf16 v[96:99], v[218:221], v[176:179], v[96:99]
	v_mfma_f32_16x16x32_bf16 v[100:103], v[210:213], v[176:179], v[100:103]
	v_mfma_f32_16x16x32_bf16 v[84:87], v[210:213], v[184:187], v[84:87]
	v_mfma_f32_16x16x32_bf16 v[80:83], v[218:221], v[184:187], v[80:83]
	v_mfma_f32_16x16x32_bf16 v[64:67], v[218:221], v[202:205], v[64:67]
	v_mfma_f32_16x16x32_bf16 v[68:71], v[210:213], v[202:205], v[68:71]
	s_mov_b32 m0, s27
	s_add_u32 s82, s18, 0x80
	s_addc_u32 s83, s19, 0
	s_barrier
	ds_read_b128 v[164:167], v150 offset:16384
	ds_read_b128 v[168:171], v150 offset:17408
	ds_read_b128 v[172:175], v150 offset:18432
	ds_read_b128 v[176:179], v150 offset:19456
	ds_read_b128 v[180:183], v150 offset:20480
	ds_read_b128 v[184:187], v150 offset:21504
	ds_read_b128 v[188:191], v150 offset:22528
	global_load_lds_dwordx4 v128, s[18:19]
	s_mov_b32 m0, s28
	ds_read_b128 v[202:205], v150 offset:23552
	global_load_lds_dwordx4 v130, s[18:19]
	s_barrier
	s_waitcnt lgkmcnt(0)
	v_mfma_f32_16x16x32_bf16 v[60:63], v[138:141], v[164:167], v[60:63]
	v_mfma_f32_16x16x32_bf16 v[56:59], v[156:159], v[164:167], v[56:59]
	v_mfma_f32_16x16x32_bf16 v[40:43], v[156:159], v[172:175], v[40:43]
	v_mfma_f32_16x16x32_bf16 v[44:47], v[138:141], v[172:175], v[44:47]
	v_mfma_f32_16x16x32_bf16 v[28:31], v[138:141], v[180:183], v[28:31]
	v_mfma_f32_16x16x32_bf16 v[24:27], v[156:159], v[180:183], v[24:27]
	v_mfma_f32_16x16x32_bf16 v[8:11], v[156:159], v[188:191], v[8:11]
	v_mfma_f32_16x16x32_bf16 v[12:15], v[138:141], v[188:191], v[12:15]
	v_mfma_f32_16x16x32_bf16 v[60:63], v[152:155], v[168:171], v[60:63]
	v_mfma_f32_16x16x32_bf16 v[56:59], v[160:163], v[168:171], v[56:59]
	v_mfma_f32_16x16x32_bf16 v[40:43], v[160:163], v[176:179], v[40:43]
	v_mfma_f32_16x16x32_bf16 v[44:47], v[152:155], v[176:179], v[44:47]
	v_mfma_f32_16x16x32_bf16 v[28:31], v[152:155], v[184:187], v[28:31]
	v_mfma_f32_16x16x32_bf16 v[24:27], v[160:163], v[184:187], v[24:27]
	v_mfma_f32_16x16x32_bf16 v[8:11], v[160:163], v[202:205], v[8:11]
	v_mfma_f32_16x16x32_bf16 v[12:15], v[152:155], v[202:205], v[12:15]
	s_barrier
	s_add_u32 s20, s20, s2
	s_addc_u32 s21, s21, s3
	s_add_u32 s84, s20, 0x80
	s_mov_b32 m0, s87
	s_addc_u32 s85, s21, 0
	global_load_lds_dwordx4 v194, s[20:21]
	s_add_i32 m0, s87, 0x2000
	s_nop 0
	global_load_lds_dwordx4 v132, s[20:21]
	s_waitcnt vmcnt(6)
	s_barrier
; #define PG8_STAGE(bufoff, gbase, voff) do { _Pragma("unroll") for (int _i = 0; _i < 2; ++_i) \
;         __builtin_amdgcn_global_load_lds((const unsigned*)((const char*)(gbase) + (voff)[_i]), (LAS unsigned*)(lds + (bufoff) + ldsw + _i * 8192), 16, 0, 0); } while (0)
; #define PG8_LDA(dst, b, h) do { _Pragma("unroll") for (int m = 0; m < 4; ++m) _Pragma("unroll") for (int k = 0; k < 2; ++k) dst[m][k] = *(const LAS bf16x8*)(lds + PG8_SA(b, h) + aoff + m * 2048 + k * 1024); } while (0)
; #define PG8_LDB(dst, b, h) do { _Pragma("unroll") for (int n = 0; n < 2; ++n) _Pragma("unroll") for (int k = 0; k < 2; ++k) dst[n][k] = *(const LAS bf16x8*)(lds + PG8_SB(b, h) + boff + n * 2048 + k * 1024); } while (0)
; #define PG8_MMA(ai, bj, At, Bt) do { __builtin_amdgcn_s_setprio(1); _Pragma("unroll") for (int m = 0; m < 4; ++m) _Pragma("unroll") for (int n = 0; n < 2; ++n) _Pragma("unroll") for (int k = 0; k < 2; ++k) \
;         acc[ai][bj][m][n] = __builtin_amdgcn_mfma_f32_16x16x32_bf16(Bt[n][k], At[m][k], acc[ai][bj][m][n], 0, 0, 0); __builtin_amdgcn_s_setprio(0); } while (0)
; #define PG8_WAIT_V(n) asm volatile("s_waitcnt vmcnt(" #n ")" ::: "memory")
; #define PG8_WAIT_L(n) asm volatile("s_waitcnt lgkmcnt(" #n ")" ::: "memory")
; #define PG8_BAR __builtin_amdgcn_s_barrier()
; #define PG8_SCHED __builtin_amdgcn_sched_barrier(0)
; template <class Epi>
; __device__ __forceinline__ void gemm_phase(LAS unsigned char* lds, const Gemm g, const StaticOrder& S, const Epi& E) {
;     ...
;             PG8_WAIT_V(6); PG8_BAR; PG8_MMA(1, 1, At, B1); PG8_BAR;
;             PG8_LDB(B0, 1, 0); PG8_SCHED; PG8_LDA(At, 1, 0); PG8_STAGE(PG8_SA(0, 1), a2 + hstep, voffA);
;             PG8_WAIT_L(8); PG8_BAR; PG8_WAIT_L(0); PG8_MMA(0, 0, At, B0); PG8_BAR; PG8_SCHED;
;             PG8_LDB(B1, 1, 1); PG8_STAGE(PG8_SB(1, 0), b3, voffB);
	v_mfma_f32_16x16x32_bf16 v[52:55], v[206:209], v[164:167], v[52:55]
	v_mfma_f32_16x16x32_bf16 v[48:51], v[214:217], v[164:167], v[48:51]
	v_mfma_f32_16x16x32_bf16 v[32:35], v[214:217], v[172:175], v[32:35]
	v_mfma_f32_16x16x32_bf16 v[36:39], v[206:209], v[172:175], v[36:39]
	v_mfma_f32_16x16x32_bf16 v[20:23], v[206:209], v[180:183], v[20:23]
	v_mfma_f32_16x16x32_bf16 v[16:19], v[214:217], v[180:183], v[16:19]
	v_mfma_f32_16x16x32_bf16 v[0:3], v[214:217], v[188:191], v[0:3]
	v_mfma_f32_16x16x32_bf16 v[4:7], v[206:209], v[188:191], v[4:7]
	v_mfma_f32_16x16x32_bf16 v[52:55], v[210:213], v[168:171], v[52:55]
	v_mfma_f32_16x16x32_bf16 v[48:51], v[218:221], v[168:171], v[48:51]
	v_mfma_f32_16x16x32_bf16 v[32:35], v[218:221], v[176:179], v[32:35]
	v_mfma_f32_16x16x32_bf16 v[36:39], v[210:213], v[176:179], v[36:39]
	v_mfma_f32_16x16x32_bf16 v[20:23], v[210:213], v[184:187], v[20:23]
	v_mfma_f32_16x16x32_bf16 v[16:19], v[218:221], v[184:187], v[16:19]
	v_mfma_f32_16x16x32_bf16 v[0:3], v[218:221], v[202:205], v[0:3]
	v_mfma_f32_16x16x32_bf16 v[4:7], v[210:213], v[202:205], v[4:7]
	s_barrier
	ds_read_b128 v[138:141], v226
	ds_read_b128 v[152:155], v226 offset:1024
	ds_read_b128 v[156:159], v226 offset:2048
	ds_read_b128 v[160:163], v226 offset:3072
	s_add_u32 s18, s18, s2
	s_addc_u32 s19, s19, s3
	s_mov_b32 m0, s29
	ds_read_b128 v[164:167], v150 offset:32768
	ds_read_b128 v[168:171], v150 offset:33792
	ds_read_b128 v[172:175], v150 offset:34816
	ds_read_b128 v[176:179], v150 offset:35840
	ds_read_b128 v[180:183], v150 offset:36864
	ds_read_b128 v[184:187], v150 offset:37888
	ds_read_b128 v[188:191], v150 offset:38912
	global_load_lds_dwordx4 v128, s[18:19]
	s_mov_b32 m0, s30
	ds_read_b128 v[202:205], v150 offset:39936
	global_load_lds_dwordx4 v130, s[18:19]
	s_waitcnt lgkmcnt(8)
	s_barrier
	s_waitcnt lgkmcnt(0)
	v_mfma_f32_16x16x32_bf16 v[124:127], v[138:141], v[164:167], v[124:127]
	v_mfma_f32_16x16x32_bf16 v[120:123], v[156:159], v[164:167], v[120:123]
	v_mfma_f32_16x16x32_bf16 v[104:107], v[156:159], v[172:175], v[104:107]
	v_mfma_f32_16x16x32_bf16 v[108:111], v[138:141], v[172:175], v[108:111]
	v_mfma_f32_16x16x32_bf16 v[92:95], v[138:141], v[180:183], v[92:95]
	v_mfma_f32_16x16x32_bf16 v[88:91], v[156:159], v[180:183], v[88:91]
	v_mfma_f32_16x16x32_bf16 v[72:75], v[156:159], v[188:191], v[72:75]
	v_mfma_f32_16x16x32_bf16 v[76:79], v[138:141], v[188:191], v[76:79]
	v_mfma_f32_16x16x32_bf16 v[124:127], v[152:155], v[168:171], v[124:127]
	v_mfma_f32_16x16x32_bf16 v[120:123], v[160:163], v[168:171], v[120:123]
	v_mfma_f32_16x16x32_bf16 v[104:107], v[160:163], v[176:179], v[104:107]
	v_mfma_f32_16x16x32_bf16 v[108:111], v[152:155], v[176:179], v[108:111]
	v_mfma_f32_16x16x32_bf16 v[92:95], v[152:155], v[184:187], v[92:95]
	v_mfma_f32_16x16x32_bf16 v[88:91], v[160:163], v[184:187], v[88:91]
	v_mfma_f32_16x16x32_bf16 v[72:75], v[160:163], v[202:205], v[72:75]
	v_mfma_f32_16x16x32_bf16 v[76:79], v[152:155], v[202:205], v[76:79]
	s_barrier
	s_mov_b32 m0, s88
	ds_read_b128 v[206:209], v227
	ds_read_b128 v[210:213], v227 offset:1024
	ds_read_b128 v[214:217], v227 offset:2048
	global_load_lds_dwordx4 v194, s[80:81]
	s_add_i32 m0, s88, 0x2000
	ds_read_b128 v[218:221], v227 offset:3072
	global_load_lds_dwordx4 v132, s[80:81]
	s_barrier
; #define PG8_STAGE(bufoff, gbase, voff) do { _Pragma("unroll") for (int _i = 0; _i < 2; ++_i) \
;         __builtin_amdgcn_global_load_lds((const unsigned*)((const char*)(gbase) + (voff)[_i]), (LAS unsigned*)(lds + (bufoff) + ldsw + _i * 8192), 16, 0, 0); } while (0)
; #define PG8_LDA(dst, b, h) do { _Pragma("unroll") for (int m = 0; m < 4; ++m) _Pragma("unroll") for (int k = 0; k < 2; ++k) dst[m][k] = *(const LAS bf16x8*)(lds + PG8_SA(b, h) + aoff + m * 2048 + k * 1024); } while (0)
; #define PG8_MMA(ai, bj, At, Bt) do { __builtin_amdgcn_s_setprio(1); _Pragma("unroll") for (int m = 0; m < 4; ++m) _Pragma("unroll") for (int n = 0; n < 2; ++n) _Pragma("unroll") for (int k = 0; k < 2; ++k) \
;         acc[ai][bj][m][n] = __builtin_amdgcn_mfma_f32_16x16x32_bf16(Bt[n][k], At[m][k], acc[ai][bj][m][n], 0, 0, 0); __builtin_amdgcn_s_setprio(0); } while (0)
; #define PG8_WAIT_V(n) asm volatile("s_waitcnt vmcnt(" #n ")" ::: "memory")
; #define PG8_WAIT_L(n) asm volatile("s_waitcnt lgkmcnt(" #n ")" ::: "memory")
; #define PG8_BAR __builtin_amdgcn_s_barrier()
; #define PG8_SCHED __builtin_amdgcn_sched_barrier(0)
; template <class Epi>
; __device__ __forceinline__ void gemm_phase(LAS unsigned char* lds, const Gemm g, const StaticOrder& S, const Epi& E) {
;     ...
;             PG8_BAR; PG8_WAIT_L(0); PG8_MMA(0, 1, At, B1); PG8_BAR;
;             PG8_LDA(At, 1, 1); PG8_STAGE(PG8_SA(1, 0), a3, voffA);
;             PG8_BAR; PG8_WAIT_L(0); PG8_MMA(1, 0, At, B0); PG8_BAR; PG8_SCHED;
;             PG8_STAGE(PG8_SB(1, 1), b3 + hstep, voffB);
;             PG8_WAIT_V(6); PG8_BAR; PG8_MMA(1, 1, At, B1); PG8_BAR;
;         }
	s_waitcnt lgkmcnt(0)
	v_mfma_f32_16x16x32_bf16 v[116:119], v[206:209], v[164:167], v[116:119]
	v_mfma_f32_16x16x32_bf16 v[112:115], v[214:217], v[164:167], v[112:115]
	v_mfma_f32_16x16x32_bf16 v[96:99], v[214:217], v[172:175], v[96:99]
	v_mfma_f32_16x16x32_bf16 v[100:103], v[206:209], v[172:175], v[100:103]
	v_mfma_f32_16x16x32_bf16 v[84:87], v[206:209], v[180:183], v[84:87]
	v_mfma_f32_16x16x32_bf16 v[80:83], v[214:217], v[180:183], v[80:83]
	v_mfma_f32_16x16x32_bf16 v[64:67], v[214:217], v[188:191], v[64:67]
	v_mfma_f32_16x16x32_bf16 v[68:71], v[206:209], v[188:191], v[68:71]
	v_mfma_f32_16x16x32_bf16 v[116:119], v[210:213], v[168:171], v[116:119]
	v_mfma_f32_16x16x32_bf16 v[112:115], v[218:221], v[168:171], v[112:115]
	v_mfma_f32_16x16x32_bf16 v[96:99], v[218:221], v[176:179], v[96:99]
	v_mfma_f32_16x16x32_bf16 v[100:103], v[210:213], v[176:179], v[100:103]
	v_mfma_f32_16x16x32_bf16 v[84:87], v[210:213], v[184:187], v[84:87]
	v_mfma_f32_16x16x32_bf16 v[80:83], v[218:221], v[184:187], v[80:83]
	v_mfma_f32_16x16x32_bf16 v[64:67], v[218:221], v[202:205], v[64:67]
	v_mfma_f32_16x16x32_bf16 v[68:71], v[210:213], v[202:205], v[68:71]
	s_mov_b32 m0, s31
	s_barrier
	ds_read_b128 v[164:167], v150 offset:49152
	ds_read_b128 v[168:171], v150 offset:50176
	ds_read_b128 v[172:175], v150 offset:51200
	ds_read_b128 v[176:179], v150 offset:52224
	ds_read_b128 v[180:183], v150 offset:53248
	ds_read_b128 v[184:187], v150 offset:54272
	ds_read_b128 v[188:191], v150 offset:55296
	global_load_lds_dwordx4 v128, s[82:83]
	s_mov_b32 m0, s33
	ds_read_b128 v[202:205], v150 offset:56320
	global_load_lds_dwordx4 v130, s[82:83]
	s_barrier
	s_waitcnt lgkmcnt(0)
	v_mfma_f32_16x16x32_bf16 v[60:63], v[138:141], v[164:167], v[60:63]
	v_mfma_f32_16x16x32_bf16 v[56:59], v[156:159], v[164:167], v[56:59]
	v_mfma_f32_16x16x32_bf16 v[40:43], v[156:159], v[172:175], v[40:43]
	v_mfma_f32_16x16x32_bf16 v[44:47], v[138:141], v[172:175], v[44:47]
	v_mfma_f32_16x16x32_bf16 v[28:31], v[138:141], v[180:183], v[28:31]
	v_mfma_f32_16x16x32_bf16 v[24:27], v[156:159], v[180:183], v[24:27]
	v_mfma_f32_16x16x32_bf16 v[8:11], v[156:159], v[188:191], v[8:11]
	v_mfma_f32_16x16x32_bf16 v[12:15], v[138:141], v[188:191], v[12:15]
	v_mfma_f32_16x16x32_bf16 v[60:63], v[152:155], v[168:171], v[60:63]
	v_mfma_f32_16x16x32_bf16 v[56:59], v[160:163], v[168:171], v[56:59]
	v_mfma_f32_16x16x32_bf16 v[40:43], v[160:163], v[176:179], v[40:43]
	v_mfma_f32_16x16x32_bf16 v[44:47], v[152:155], v[176:179], v[44:47]
	v_mfma_f32_16x16x32_bf16 v[28:31], v[152:155], v[184:187], v[28:31]
	v_mfma_f32_16x16x32_bf16 v[24:27], v[160:163], v[184:187], v[24:27]
	v_mfma_f32_16x16x32_bf16 v[8:11], v[160:163], v[202:205], v[8:11]
	v_mfma_f32_16x16x32_bf16 v[12:15], v[152:155], v[202:205], v[12:15]
	s_barrier
	s_mov_b32 m0, s89
	s_nop 0
	global_load_lds_dwordx4 v194, s[84:85]
	s_add_i32 m0, s89, 0x2000
	s_nop 0
	global_load_lds_dwordx4 v132, s[84:85]
	s_waitcnt vmcnt(6)
	s_barrier
	v_mfma_f32_16x16x32_bf16 v[52:55], v[206:209], v[164:167], v[52:55]
	v_mfma_f32_16x16x32_bf16 v[48:51], v[214:217], v[164:167], v[48:51]
	v_mfma_f32_16x16x32_bf16 v[32:35], v[214:217], v[172:175], v[32:35]
	v_mfma_f32_16x16x32_bf16 v[36:39], v[206:209], v[172:175], v[36:39]
	v_mfma_f32_16x16x32_bf16 v[20:23], v[206:209], v[180:183], v[20:23]
	v_mfma_f32_16x16x32_bf16 v[16:19], v[214:217], v[180:183], v[16:19]
	v_mfma_f32_16x16x32_bf16 v[0:3], v[214:217], v[188:191], v[0:3]
	v_mfma_f32_16x16x32_bf16 v[4:7], v[206:209], v[188:191], v[4:7]
	v_mfma_f32_16x16x32_bf16 v[52:55], v[210:213], v[168:171], v[52:55]
	v_mfma_f32_16x16x32_bf16 v[48:51], v[218:221], v[168:171], v[48:51]
	v_mfma_f32_16x16x32_bf16 v[32:35], v[218:221], v[176:179], v[32:35]
	v_mfma_f32_16x16x32_bf16 v[36:39], v[210:213], v[176:179], v[36:39]
	v_mfma_f32_16x16x32_bf16 v[20:23], v[210:213], v[184:187], v[20:23]
	v_mfma_f32_16x16x32_bf16 v[16:19], v[218:221], v[184:187], v[16:19]
	v_mfma_f32_16x16x32_bf16 v[0:3], v[218:221], v[202:205], v[0:3]
	v_mfma_f32_16x16x32_bf16 v[4:7], v[210:213], v[202:205], v[4:7]
	s_add_u32 s42, s42, 0x100
	s_addc_u32 s43, s43, 0
	s_add_u32 s16, s16, 0x100
	s_addc_u32 s17, s17, 0
	s_cmp_ge_i32 s44, s34
	s_mov_b32 s18, s44
	s_barrier
	s_cbranch_scc0 .LBB0_165

; #define PG8_STAGE(bufoff, gbase, voff) do { _Pragma("unroll") for (int _i = 0; _i < 2; ++_i) \
;         __builtin_amdgcn_global_load_lds((const unsigned*)((const char*)(gbase) + (voff)[_i]), (LAS unsigned*)(lds + (bufoff) + ldsw + _i * 8192), 16, 0, 0); } while (0)
; #define PG8_LDA(dst, b, h) do { _Pragma("unroll") for (int m = 0; m < 4; ++m) _Pragma("unroll") for (int k = 0; k < 2; ++k) dst[m][k] = *(const LAS bf16x8*)(lds + PG8_SA(b, h) + aoff + m * 2048 + k * 1024); } while (0)
; #define PG8_LDB(dst, b, h) do { _Pragma("unroll") for (int n = 0; n < 2; ++n) _Pragma("unroll") for (int k = 0; k < 2; ++k) dst[n][k] = *(const LAS bf16x8*)(lds + PG8_SB(b, h) + boff + n * 2048 + k * 1024); } while (0)
; #define PG8_MMA(ai, bj, At, Bt) do { __builtin_amdgcn_s_setprio(1); _Pragma("unroll") for (int m = 0; m < 4; ++m) _Pragma("unroll") for (int n = 0; n < 2; ++n) _Pragma("unroll") for (int k = 0; k < 2; ++k) \
;         acc[ai][bj][m][n] = __builtin_amdgcn_mfma_f32_16x16x32_bf16(Bt[n][k], At[m][k], acc[ai][bj][m][n], 0, 0, 0); __builtin_amdgcn_s_setprio(0); } while (0)
; #define PG8_WAIT_V(n) asm volatile("s_waitcnt vmcnt(" #n ")" ::: "memory")
; #define PG8_WAIT_L(n) asm volatile("s_waitcnt lgkmcnt(" #n ")" ::: "memory")
; template <class Epi>
; __device__ __forceinline__ void gemm_phase(LAS unsigned char* lds, const Gemm g, const StaticOrder& S, const Epi& E) {
;     ...
;         for (int t = 0; t < nt; t += 2) {
;             const bool last = (t == nt - 2);
;             const char* a1 = cA + (size_t)(t + 1) * kstep;
;             const char* a2 = last ? nA : cA + (size_t)(t + 2) * kstep; const char* b2 = last ? nB : cB + (size_t)(t + 2) * kstep;
;             const char* a3 = a2 + kstep; const char* b3 = b2 + kstep;
;             PG8_LDB(B0, 0, 0); PG8_SCHED; PG8_LDA(At, 0, 0); PG8_STAGE(PG8_SA(1, 1), a1 + hstep, voffA);
;             PG8_WAIT_L(8); PG8_BAR; PG8_WAIT_L(0); PG8_MMA(0, 0, At, B0); PG8_BAR; PG8_SCHED;
;             PG8_LDB(B1, 0, 1); PG8_STAGE(PG8_SB(0, 0), b2, voffB);
;             PG8_BAR; PG8_WAIT_L(0); PG8_MMA(0, 1, At, B1); PG8_BAR;
;             PG8_LDA(At, 0, 1); PG8_STAGE(PG8_SA(0, 0), a2, voffA);
;             PG8_BAR; PG8_WAIT_L(0); PG8_MMA(1, 0, At, B0); PG8_BAR; PG8_SCHED;
;             PG8_STAGE(PG8_SB(0, 1), b2 + hstep, voffB);
;             PG8_WAIT_V(6); PG8_BAR; PG8_MMA(1, 1, At, B1); PG8_BAR;
.LBB0_528:
	s_add_i32 s42, s18, 2
	s_add_u32 s20, s16, 0x80
	s_addc_u32 s19, s17, 0
	ds_read_b128 v[138:141], v224
	ds_read_b128 v[150:153], v224 offset:1024
	ds_read_b128 v[154:157], v224 offset:2048
	ds_read_b128 v[158:161], v224 offset:3072
	s_cmp_eq_u32 s33, s18
	s_cselect_b32 s18, s10, s20
	s_cselect_b32 s19, s11, s19
	s_cselect_b32 s21, s13, s41
	s_cselect_b32 s20, s12, s40
	s_add_i32 m0, s25, 0xc000
	ds_read_b128 v[162:165], v148
	ds_read_b128 v[166:169], v148 offset:1024
	ds_read_b128 v[170:173], v148 offset:2048
	ds_read_b128 v[174:177], v148 offset:3072
	ds_read_b128 v[178:181], v148 offset:4096
	ds_read_b128 v[182:185], v148 offset:5120
	ds_read_b128 v[186:189], v148 offset:6144
	global_load_lds_dwordx4 v136, s[16:17]
	s_add_i32 m0, s25, 0xe000
	ds_read_b128 v[202:205], v148 offset:7168
	global_load_lds_dwordx4 v134, s[16:17]
	s_waitcnt lgkmcnt(8)
	s_barrier
	s_waitcnt lgkmcnt(0)
	v_mfma_f32_16x16x32_bf16 v[124:127], v[138:141], v[162:165], v[124:127]
	v_mfma_f32_16x16x32_bf16 v[120:123], v[154:157], v[162:165], v[120:123]
	v_mfma_f32_16x16x32_bf16 v[104:107], v[154:157], v[170:173], v[104:107]
	v_mfma_f32_16x16x32_bf16 v[108:111], v[138:141], v[170:173], v[108:111]
	v_mfma_f32_16x16x32_bf16 v[92:95], v[138:141], v[178:181], v[92:95]
	v_mfma_f32_16x16x32_bf16 v[88:91], v[154:157], v[178:181], v[88:91]
	v_mfma_f32_16x16x32_bf16 v[72:75], v[154:157], v[186:189], v[72:75]
	v_mfma_f32_16x16x32_bf16 v[76:79], v[138:141], v[186:189], v[76:79]
	v_mfma_f32_16x16x32_bf16 v[124:127], v[150:153], v[166:169], v[124:127]
	v_mfma_f32_16x16x32_bf16 v[120:123], v[158:161], v[166:169], v[120:123]
	v_mfma_f32_16x16x32_bf16 v[104:107], v[158:161], v[174:177], v[104:107]
	v_mfma_f32_16x16x32_bf16 v[108:111], v[150:153], v[174:177], v[108:111]
	v_mfma_f32_16x16x32_bf16 v[92:95], v[150:153], v[182:185], v[92:95]
	v_mfma_f32_16x16x32_bf16 v[88:91], v[158:161], v[182:185], v[88:91]
	v_mfma_f32_16x16x32_bf16 v[72:75], v[158:161], v[202:205], v[72:75]
	v_mfma_f32_16x16x32_bf16 v[76:79], v[150:153], v[202:205], v[76:79]
	s_barrier
	s_add_u32 s80, s20, 0x80
	s_addc_u32 s81, s21, 0
	s_mov_b32 m0, s86
	ds_read_b128 v[206:209], v225
	ds_read_b128 v[210:213], v225 offset:1024
	ds_read_b128 v[214:217], v225 offset:2048
	global_load_lds_dwordx4 v194, s[20:21]
	s_add_i32 m0, s86, 0x2000
	ds_read_b128 v[218:221], v225 offset:3072
	global_load_lds_dwordx4 v132, s[20:21]
	s_barrier
	s_waitcnt lgkmcnt(0)
	v_mfma_f32_16x16x32_bf16 v[116:119], v[206:209], v[162:165], v[116:119]
	v_mfma_f32_16x16x32_bf16 v[112:115], v[214:217], v[162:165], v[112:115]
	v_mfma_f32_16x16x32_bf16 v[96:99], v[214:217], v[170:173], v[96:99]
	v_mfma_f32_16x16x32_bf16 v[100:103], v[206:209], v[170:173], v[100:103]
	v_mfma_f32_16x16x32_bf16 v[84:87], v[206:209], v[178:181], v[84:87]
	v_mfma_f32_16x16x32_bf16 v[80:83], v[214:217], v[178:181], v[80:83]
	v_mfma_f32_16x16x32_bf16 v[64:67], v[214:217], v[186:189], v[64:67]
	v_mfma_f32_16x16x32_bf16 v[68:71], v[206:209], v[186:189], v[68:71]
	v_mfma_f32_16x16x32_bf16 v[116:119], v[210:213], v[166:169], v[116:119]
	v_mfma_f32_16x16x32_bf16 v[112:115], v[218:221], v[166:169], v[112:115]
	v_mfma_f32_16x16x32_bf16 v[96:99], v[218:221], v[174:177], v[96:99]
	v_mfma_f32_16x16x32_bf16 v[100:103], v[210:213], v[174:177], v[100:103]
	v_mfma_f32_16x16x32_bf16 v[84:87], v[210:213], v[182:185], v[84:87]
	v_mfma_f32_16x16x32_bf16 v[80:83], v[218:221], v[182:185], v[80:83]
	v_mfma_f32_16x16x32_bf16 v[64:67], v[218:221], v[202:205], v[64:67]
	v_mfma_f32_16x16x32_bf16 v[68:71], v[210:213], v[202:205], v[68:71]
	s_mov_b32 m0, s25
	s_add_u32 s82, s18, 0x80
	s_addc_u32 s83, s19, 0
	s_barrier
	ds_read_b128 v[162:165], v148 offset:16384
	ds_read_b128 v[166:169], v148 offset:17408
	ds_read_b128 v[170:173], v148 offset:18432
	ds_read_b128 v[174:177], v148 offset:19456
	ds_read_b128 v[178:181], v148 offset:20480
	ds_read_b128 v[182:185], v148 offset:21504
	ds_read_b128 v[186:189], v148 offset:22528
	global_load_lds_dwordx4 v128, s[18:19]
	s_mov_b32 m0, s26
	ds_read_b128 v[202:205], v148 offset:23552
	global_load_lds_dwordx4 v130, s[18:19]
	s_barrier
	s_waitcnt lgkmcnt(0)
	v_mfma_f32_16x16x32_bf16 v[60:63], v[138:141], v[162:165], v[60:63]
	v_mfma_f32_16x16x32_bf16 v[56:59], v[154:157], v[162:165], v[56:59]
	v_mfma_f32_16x16x32_bf16 v[40:43], v[154:157], v[170:173], v[40:43]
	v_mfma_f32_16x16x32_bf16 v[44:47], v[138:141], v[170:173], v[44:47]
	v_mfma_f32_16x16x32_bf16 v[28:31], v[138:141], v[178:181], v[28:31]
	v_mfma_f32_16x16x32_bf16 v[24:27], v[154:157], v[178:181], v[24:27]
	v_mfma_f32_16x16x32_bf16 v[8:11], v[154:157], v[186:189], v[8:11]
	v_mfma_f32_16x16x32_bf16 v[12:15], v[138:141], v[186:189], v[12:15]
	v_mfma_f32_16x16x32_bf16 v[60:63], v[150:153], v[166:169], v[60:63]
	v_mfma_f32_16x16x32_bf16 v[56:59], v[158:161], v[166:169], v[56:59]
	v_mfma_f32_16x16x32_bf16 v[40:43], v[158:161], v[174:177], v[40:43]
	v_mfma_f32_16x16x32_bf16 v[44:47], v[150:153], v[174:177], v[44:47]
	v_mfma_f32_16x16x32_bf16 v[28:31], v[150:153], v[182:185], v[28:31]
	v_mfma_f32_16x16x32_bf16 v[24:27], v[158:161], v[182:185], v[24:27]
	v_mfma_f32_16x16x32_bf16 v[8:11], v[158:161], v[202:205], v[8:11]
	v_mfma_f32_16x16x32_bf16 v[12:15], v[150:153], v[202:205], v[12:15]
	s_barrier
	s_add_u32 s20, s20, s2
	s_addc_u32 s21, s21, s3
	s_add_u32 s84, s20, 0x80
	s_mov_b32 m0, s87
	s_addc_u32 s85, s21, 0
	global_load_lds_dwordx4 v194, s[20:21]
	s_add_i32 m0, s87, 0x2000
	s_nop 0
	global_load_lds_dwordx4 v132, s[20:21]
	s_waitcnt vmcnt(6)
	s_barrier
; #define PG8_STAGE(bufoff, gbase, voff) do { _Pragma("unroll") for (int _i = 0; _i < 2; ++_i) \
;         __builtin_amdgcn_global_load_lds((const unsigned*)((const char*)(gbase) + (voff)[_i]), (LAS unsigned*)(lds + (bufoff) + ldsw + _i * 8192), 16, 0, 0); } while (0)
; #define PG8_LDA(dst, b, h) do { _Pragma("unroll") for (int m = 0; m < 4; ++m) _Pragma("unroll") for (int k = 0; k < 2; ++k) dst[m][k] = *(const LAS bf16x8*)(lds + PG8_SA(b, h) + aoff + m * 2048 + k * 1024); } while (0)
; #define PG8_LDB(dst, b, h) do { _Pragma("unroll") for (int n = 0; n < 2; ++n) _Pragma("unroll") for (int k = 0; k < 2; ++k) dst[n][k] = *(const LAS bf16x8*)(lds + PG8_SB(b, h) + boff + n * 2048 + k * 1024); } while (0)
; #define PG8_MMA(ai, bj, At, Bt) do { __builtin_amdgcn_s_setprio(1); _Pragma("unroll") for (int m = 0; m < 4; ++m) _Pragma("unroll") for (int n = 0; n < 2; ++n) _Pragma("unroll") for (int k = 0; k < 2; ++k) \
;         acc[ai][bj][m][n] = __builtin_amdgcn_mfma_f32_16x16x32_bf16(Bt[n][k], At[m][k], acc[ai][bj][m][n], 0, 0, 0); __builtin_amdgcn_s_setprio(0); } while (0)
; #define PG8_WAIT_V(n) asm volatile("s_waitcnt vmcnt(" #n ")" ::: "memory")
; #define PG8_WAIT_L(n) asm volatile("s_waitcnt lgkmcnt(" #n ")" ::: "memory")
; #define PG8_BAR __builtin_amdgcn_s_barrier()
; #define PG8_SCHED __builtin_amdgcn_sched_barrier(0)
; template <class Epi>
; __device__ __forceinline__ void gemm_phase(LAS unsigned char* lds, const Gemm g, const StaticOrder& S, const Epi& E) {
;     ...
;             PG8_WAIT_V(6); PG8_BAR; PG8_MMA(1, 1, At, B1); PG8_BAR;
;             PG8_LDB(B0, 1, 0); PG8_SCHED; PG8_LDA(At, 1, 0); PG8_STAGE(PG8_SA(0, 1), a2 + hstep, voffA);
;             PG8_WAIT_L(8); PG8_BAR; PG8_WAIT_L(0); PG8_MMA(0, 0, At, B0); PG8_BAR; PG8_SCHED;
;             PG8_LDB(B1, 1, 1); PG8_STAGE(PG8_SB(1, 0), b3, voffB);
	v_mfma_f32_16x16x32_bf16 v[52:55], v[206:209], v[162:165], v[52:55]
	v_mfma_f32_16x16x32_bf16 v[48:51], v[214:217], v[162:165], v[48:51]
	v_mfma_f32_16x16x32_bf16 v[32:35], v[214:217], v[170:173], v[32:35]
	v_mfma_f32_16x16x32_bf16 v[36:39], v[206:209], v[170:173], v[36:39]
	v_mfma_f32_16x16x32_bf16 v[20:23], v[206:209], v[178:181], v[20:23]
	v_mfma_f32_16x16x32_bf16 v[16:19], v[214:217], v[178:181], v[16:19]
	v_mfma_f32_16x16x32_bf16 v[0:3], v[214:217], v[186:189], v[0:3]
	v_mfma_f32_16x16x32_bf16 v[4:7], v[206:209], v[186:189], v[4:7]
	v_mfma_f32_16x16x32_bf16 v[52:55], v[210:213], v[166:169], v[52:55]
	v_mfma_f32_16x16x32_bf16 v[48:51], v[218:221], v[166:169], v[48:51]
	v_mfma_f32_16x16x32_bf16 v[32:35], v[218:221], v[174:177], v[32:35]
	v_mfma_f32_16x16x32_bf16 v[36:39], v[210:213], v[174:177], v[36:39]
	v_mfma_f32_16x16x32_bf16 v[20:23], v[210:213], v[182:185], v[20:23]
	v_mfma_f32_16x16x32_bf16 v[16:19], v[218:221], v[182:185], v[16:19]
	v_mfma_f32_16x16x32_bf16 v[0:3], v[218:221], v[202:205], v[0:3]
	v_mfma_f32_16x16x32_bf16 v[4:7], v[210:213], v[202:205], v[4:7]
	s_barrier
	ds_read_b128 v[138:141], v226
	ds_read_b128 v[150:153], v226 offset:1024
	ds_read_b128 v[154:157], v226 offset:2048
	ds_read_b128 v[158:161], v226 offset:3072
	s_add_u32 s18, s18, s2
	s_addc_u32 s19, s19, s3
	s_mov_b32 m0, s27
	ds_read_b128 v[162:165], v148 offset:32768
	ds_read_b128 v[166:169], v148 offset:33792
	ds_read_b128 v[170:173], v148 offset:34816
	ds_read_b128 v[174:177], v148 offset:35840
	ds_read_b128 v[178:181], v148 offset:36864
	ds_read_b128 v[182:185], v148 offset:37888
	ds_read_b128 v[186:189], v148 offset:38912
	global_load_lds_dwordx4 v128, s[18:19]
	s_mov_b32 m0, s28
	ds_read_b128 v[202:205], v148 offset:39936
	global_load_lds_dwordx4 v130, s[18:19]
	s_waitcnt lgkmcnt(8)
	s_barrier
	s_waitcnt lgkmcnt(0)
	v_mfma_f32_16x16x32_bf16 v[124:127], v[138:141], v[162:165], v[124:127]
	v_mfma_f32_16x16x32_bf16 v[120:123], v[154:157], v[162:165], v[120:123]
	v_mfma_f32_16x16x32_bf16 v[104:107], v[154:157], v[170:173], v[104:107]
	v_mfma_f32_16x16x32_bf16 v[108:111], v[138:141], v[170:173], v[108:111]
	v_mfma_f32_16x16x32_bf16 v[92:95], v[138:141], v[178:181], v[92:95]
	v_mfma_f32_16x16x32_bf16 v[88:91], v[154:157], v[178:181], v[88:91]
	v_mfma_f32_16x16x32_bf16 v[72:75], v[154:157], v[186:189], v[72:75]
	v_mfma_f32_16x16x32_bf16 v[76:79], v[138:141], v[186:189], v[76:79]
	v_mfma_f32_16x16x32_bf16 v[124:127], v[150:153], v[166:169], v[124:127]
	v_mfma_f32_16x16x32_bf16 v[120:123], v[158:161], v[166:169], v[120:123]
	v_mfma_f32_16x16x32_bf16 v[104:107], v[158:161], v[174:177], v[104:107]
	v_mfma_f32_16x16x32_bf16 v[108:111], v[150:153], v[174:177], v[108:111]
	v_mfma_f32_16x16x32_bf16 v[92:95], v[150:153], v[182:185], v[92:95]
	v_mfma_f32_16x16x32_bf16 v[88:91], v[158:161], v[182:185], v[88:91]
	v_mfma_f32_16x16x32_bf16 v[72:75], v[158:161], v[202:205], v[72:75]
	v_mfma_f32_16x16x32_bf16 v[76:79], v[150:153], v[202:205], v[76:79]
	s_barrier
	s_mov_b32 m0, s88
	ds_read_b128 v[206:209], v227
	ds_read_b128 v[210:213], v227 offset:1024
	ds_read_b128 v[214:217], v227 offset:2048
	global_load_lds_dwordx4 v194, s[80:81]
	s_add_i32 m0, s88, 0x2000
	ds_read_b128 v[218:221], v227 offset:3072
	global_load_lds_dwordx4 v132, s[80:81]
	s_barrier
; #define PG8_STAGE(bufoff, gbase, voff) do { _Pragma("unroll") for (int _i = 0; _i < 2; ++_i) \
;         __builtin_amdgcn_global_load_lds((const unsigned*)((const char*)(gbase) + (voff)[_i]), (LAS unsigned*)(lds + (bufoff) + ldsw + _i * 8192), 16, 0, 0); } while (0)
; #define PG8_LDA(dst, b, h) do { _Pragma("unroll") for (int m = 0; m < 4; ++m) _Pragma("unroll") for (int k = 0; k < 2; ++k) dst[m][k] = *(const LAS bf16x8*)(lds + PG8_SA(b, h) + aoff + m * 2048 + k * 1024); } while (0)
; #define PG8_MMA(ai, bj, At, Bt) do { __builtin_amdgcn_s_setprio(1); _Pragma("unroll") for (int m = 0; m < 4; ++m) _Pragma("unroll") for (int n = 0; n < 2; ++n) _Pragma("unroll") for (int k = 0; k < 2; ++k) \
;         acc[ai][bj][m][n] = __builtin_amdgcn_mfma_f32_16x16x32_bf16(Bt[n][k], At[m][k], acc[ai][bj][m][n], 0, 0, 0); __builtin_amdgcn_s_setprio(0); } while (0)
; #define PG8_WAIT_V(n) asm volatile("s_waitcnt vmcnt(" #n ")" ::: "memory")
; #define PG8_WAIT_L(n) asm volatile("s_waitcnt lgkmcnt(" #n ")" ::: "memory")
; #define PG8_BAR __builtin_amdgcn_s_barrier()
; #define PG8_SCHED __builtin_amdgcn_sched_barrier(0)
; template <class Epi>
; __device__ __forceinline__ void gemm_phase(LAS unsigned char* lds, const Gemm g, const StaticOrder& S, const Epi& E) {
;     ...
;             PG8_BAR; PG8_WAIT_L(0); PG8_MMA(0, 1, At, B1); PG8_BAR;
;             PG8_LDA(At, 1, 1); PG8_STAGE(PG8_SA(1, 0), a3, voffA);
;             PG8_BAR; PG8_WAIT_L(0); PG8_MMA(1, 0, At, B0); PG8_BAR; PG8_SCHED;
;             PG8_STAGE(PG8_SB(1, 1), b3 + hstep, voffB);
;             PG8_WAIT_V(6); PG8_BAR; PG8_MMA(1, 1, At, B1); PG8_BAR;
;         }
	s_waitcnt lgkmcnt(0)
	v_mfma_f32_16x16x32_bf16 v[116:119], v[206:209], v[162:165], v[116:119]
	v_mfma_f32_16x16x32_bf16 v[112:115], v[214:217], v[162:165], v[112:115]
	v_mfma_f32_16x16x32_bf16 v[96:99], v[214:217], v[170:173], v[96:99]
	v_mfma_f32_16x16x32_bf16 v[100:103], v[206:209], v[170:173], v[100:103]
	v_mfma_f32_16x16x32_bf16 v[84:87], v[206:209], v[178:181], v[84:87]
	v_mfma_f32_16x16x32_bf16 v[80:83], v[214:217], v[178:181], v[80:83]
	v_mfma_f32_16x16x32_bf16 v[64:67], v[214:217], v[186:189], v[64:67]
	v_mfma_f32_16x16x32_bf16 v[68:71], v[206:209], v[186:189], v[68:71]
	v_mfma_f32_16x16x32_bf16 v[116:119], v[210:213], v[166:169], v[116:119]
	v_mfma_f32_16x16x32_bf16 v[112:115], v[218:221], v[166:169], v[112:115]
	v_mfma_f32_16x16x32_bf16 v[96:99], v[218:221], v[174:177], v[96:99]
	v_mfma_f32_16x16x32_bf16 v[100:103], v[210:213], v[174:177], v[100:103]
	v_mfma_f32_16x16x32_bf16 v[84:87], v[210:213], v[182:185], v[84:87]
	v_mfma_f32_16x16x32_bf16 v[80:83], v[218:221], v[182:185], v[80:83]
	v_mfma_f32_16x16x32_bf16 v[64:67], v[218:221], v[202:205], v[64:67]
	v_mfma_f32_16x16x32_bf16 v[68:71], v[210:213], v[202:205], v[68:71]
	s_mov_b32 m0, s29
	s_barrier
	ds_read_b128 v[162:165], v148 offset:49152
	ds_read_b128 v[166:169], v148 offset:50176
	ds_read_b128 v[170:173], v148 offset:51200
	ds_read_b128 v[174:177], v148 offset:52224
	ds_read_b128 v[178:181], v148 offset:53248
	ds_read_b128 v[182:185], v148 offset:54272
	ds_read_b128 v[186:189], v148 offset:55296
	global_load_lds_dwordx4 v128, s[82:83]
	s_mov_b32 m0, s30
	ds_read_b128 v[202:205], v148 offset:56320
	global_load_lds_dwordx4 v130, s[82:83]
	s_barrier
	s_waitcnt lgkmcnt(0)
	v_mfma_f32_16x16x32_bf16 v[60:63], v[138:141], v[162:165], v[60:63]
	v_mfma_f32_16x16x32_bf16 v[56:59], v[154:157], v[162:165], v[56:59]
	v_mfma_f32_16x16x32_bf16 v[40:43], v[154:157], v[170:173], v[40:43]
	v_mfma_f32_16x16x32_bf16 v[44:47], v[138:141], v[170:173], v[44:47]
	v_mfma_f32_16x16x32_bf16 v[28:31], v[138:141], v[178:181], v[28:31]
	v_mfma_f32_16x16x32_bf16 v[24:27], v[154:157], v[178:181], v[24:27]
	v_mfma_f32_16x16x32_bf16 v[8:11], v[154:157], v[186:189], v[8:11]
	v_mfma_f32_16x16x32_bf16 v[12:15], v[138:141], v[186:189], v[12:15]
	v_mfma_f32_16x16x32_bf16 v[60:63], v[150:153], v[166:169], v[60:63]
	v_mfma_f32_16x16x32_bf16 v[56:59], v[158:161], v[166:169], v[56:59]
	v_mfma_f32_16x16x32_bf16 v[40:43], v[158:161], v[174:177], v[40:43]
	v_mfma_f32_16x16x32_bf16 v[44:47], v[150:153], v[174:177], v[44:47]
	v_mfma_f32_16x16x32_bf16 v[28:31], v[150:153], v[182:185], v[28:31]
	v_mfma_f32_16x16x32_bf16 v[24:27], v[158:161], v[182:185], v[24:27]
	v_mfma_f32_16x16x32_bf16 v[8:11], v[158:161], v[202:205], v[8:11]
	v_mfma_f32_16x16x32_bf16 v[12:15], v[150:153], v[202:205], v[12:15]
	s_barrier
	s_mov_b32 m0, s89
	s_nop 0
	global_load_lds_dwordx4 v194, s[84:85]
	s_add_i32 m0, s89, 0x2000
	s_nop 0
	global_load_lds_dwordx4 v132, s[84:85]
	s_waitcnt vmcnt(6)
	s_barrier
	v_mfma_f32_16x16x32_bf16 v[52:55], v[206:209], v[162:165], v[52:55]
	v_mfma_f32_16x16x32_bf16 v[48:51], v[214:217], v[162:165], v[48:51]
	v_mfma_f32_16x16x32_bf16 v[32:35], v[214:217], v[170:173], v[32:35]
	v_mfma_f32_16x16x32_bf16 v[36:39], v[206:209], v[170:173], v[36:39]
	v_mfma_f32_16x16x32_bf16 v[20:23], v[206:209], v[178:181], v[20:23]
	v_mfma_f32_16x16x32_bf16 v[16:19], v[214:217], v[178:181], v[16:19]
	v_mfma_f32_16x16x32_bf16 v[0:3], v[214:217], v[186:189], v[0:3]
	v_mfma_f32_16x16x32_bf16 v[4:7], v[206:209], v[186:189], v[4:7]
	v_mfma_f32_16x16x32_bf16 v[52:55], v[210:213], v[166:169], v[52:55]
	v_mfma_f32_16x16x32_bf16 v[48:51], v[218:221], v[166:169], v[48:51]
	v_mfma_f32_16x16x32_bf16 v[32:35], v[218:221], v[174:177], v[32:35]
	v_mfma_f32_16x16x32_bf16 v[36:39], v[210:213], v[174:177], v[36:39]
	v_mfma_f32_16x16x32_bf16 v[20:23], v[210:213], v[182:185], v[20:23]
	v_mfma_f32_16x16x32_bf16 v[16:19], v[218:221], v[182:185], v[16:19]
	v_mfma_f32_16x16x32_bf16 v[0:3], v[218:221], v[202:205], v[0:3]
	v_mfma_f32_16x16x32_bf16 v[4:7], v[210:213], v[202:205], v[4:7]
	s_add_u32 s40, s40, 0x100
	s_addc_u32 s41, s41, 0
	s_add_u32 s16, s16, 0x100
	s_addc_u32 s17, s17, 0
	s_cmp_ge_i32 s42, s31
	s_mov_b32 s18, s42
	s_barrier
	s_cbranch_scc0 .LBB0_528
